# attention A even step: all four LDS-DMA piece issues spread over the QK phase (earlier issue = more lead before the arrival wait)
# speedup vs baseline: 1.0033x; 1.0033x over previous
; #define ATT_PKN(P, BASE, OUT) do { u32x4 w = {cvtpk(P[BASE + 0], P[BASE + 1]), cvtpk(P[BASE + 2], P[BASE + 3]), cvtpk(P[BASE + 4], P[BASE + 5]), cvtpk(P[BASE + 6], P[BASE + 7])}; OUT = *reinterpret_cast<bf16x8*>(&w); } while (0)
; __device__ __forceinline__ void finishSM(f32x16& p0, f32x16& p1, float alpha, float& l_reg, bf16x8& pa0, bf16x8& pa1, bf16x8& pa2, bf16x8& pa3) {
; #pragma unroll
;   for (int r = 0; r < 16; ++r) p1[r] = __builtin_amdgcn_exp2f(p1[r]);
;   float ps = 0;
; #pragma unroll
;   for (int r = 0; r < 16; ++r) ps += p0[r];
; #pragma unroll
;   for (int r = 0; r < 16; ++r) ps += p1[r];
;   { auto rr = __builtin_amdgcn_permlane32_swap(__float_as_uint(ps), __float_as_uint(ps), false, false);
;     ps = __uint_as_float(rr[0]) + __uint_as_float(rr[1]); }
;   l_reg = l_reg * alpha + ps;
;     ...
;   ATT_PKN(p0, 0, pa0); ATT_PKN(p0, 8, pa1); ATT_PKN(p1, 0, pa2); ATT_PKN(p1, 8, pa3);
;     ...
; }
; __device__ __forceinline__ void qkt(f32x16& p0, f32x16& p1, const bf16* Ks, const bf16x8* qr, int r32, int hi, int mp, const f32x16& negm) {
; #pragma unroll
;   for (int d0 = 0; d0 < 4; ++d0) { int cb = ((mp * 4 + d0) * 16 + hi * 8) * 2;
;     bf16x8 b0 = *reinterpret_cast<const bf16x8*>((const char*)Ks + KSWZ(r32, cb));
;     bf16x8 b1 = *reinterpret_cast<const bf16x8*>((const char*)Ks + KSWZ(32 + r32, cb));
;     if (d0 == 0) { p0 = __builtin_amdgcn_mfma_f32_32x32x16_bf16(b0, qr[0], negm, 0, 0, 0); p1 = __builtin_amdgcn_mfma_f32_32x32x16_bf16(b1, qr[0], negm, 0, 0, 0); }
;     else { p0 = __builtin_amdgcn_mfma_f32_32x32x16_bf16(b0, qr[d0], p0, 0, 0, 0); p1 = __builtin_amdgcn_mfma_f32_32x32x16_bf16(b1, qr[d0], p1, 0, 0, 0); } }
; }
; __device__ __forceinline__ void unit(const bf16* Qb, const bf16* __restrict__ Kh, const bf16* __restrict__ Vh, bf16* Ob, float lam, float post, const float* __restrict__ gsub, char* lds) {
;     ...
;   f32x16 pA0, pA1, pB0, pB1; float alA, alB; bf16x8 pa0, pa1, pa2, pa3; constexpr int NT = 4096 / KVBLK;
;   DMA_TILE(0, 0); DMA_TILE(1, 32768); DMA_TILE(2, 65536);
;   asm volatile("s_waitcnt vmcnt(0)" ::: "memory"); __syncthreads();
;   qkt(pA0, pA1, (const bf16*)(lds + 16384), qr, r32, hi, mp, negm); partialSM<true>(pA0, pA1, m_reg, negm, alA);
;   int sk = 32768, sv = 0, sw = 98304;
.Lprio_skip:
.LBB0_197:
	s_add_i32 s10, s39, 0
	s_add_i32 s13, s21, s56
	s_add_u32 s58, s50, s36
	s_addc_u32 s59, s51, s37
	s_add_u32 s60, s50, 0x4030000
	s_addc_u32 s61, s51, 0
	s_add_u32 s62, s60, 0x80
	s_addc_u32 s63, s61, 0
	v_add_u32_e32 v112, s10, v202
	ds_read_b128 v[236:239], v112 offset:24576
	ds_read_b128 v[112:115], v112 offset:16384
	v_add_u32_e32 v208, s10, v201
	ds_read_b128 v[68:71], v208 offset:24576
	ds_read_b128 v[72:75], v208 offset:16384
	v_add_u32_e32 v208, s10, v199
	v_exp_f32_e32 v210, v96
	v_add_f32_e32 v96, v174, v172
	s_waitcnt lgkmcnt(2)
	v_mfma_f32_32x32x16_bf16 v[128:143], v[112:115], v[158:161], v[80:95]
	v_add_f32_e32 v96, v175, v96
	v_add_f32_e32 v96, v211, v96
	v_mfma_f32_32x32x16_bf16 v[112:127], v[236:239], v[158:161], v[80:95]
	ds_read_b128 v[236:239], v208 offset:24576
	ds_read_b128 v[240:243], v208 offset:16384
	s_add_i32 m0, s13, 0x4000
	s_nop 0
	global_load_lds_dwordx4 v168, s[58:59]
	v_add_u32_e32 v208, s10, v183
	v_add_f32_e32 v96, v212, v96
	v_add_f32_e32 v96, v215, v96
	v_add_f32_e32 v96, v216, v96
	v_add_f32_e32 v96, v233, v96
	v_add_f32_e32 v96, v173, v96
	s_waitcnt lgkmcnt(2)
	v_mfma_f32_32x32x16_bf16 v[112:127], v[68:71], v[154:157], v[112:127]
	v_add_f32_e32 v96, v176, v96
	v_add_f32_e32 v96, v177, v96
	v_add_f32_e32 v96, v213, v96
	v_add_f32_e32 v96, v214, v96
	v_exp_f32_e32 v235, v97
	v_add_f32_e32 v96, v217, v96
	v_add_f32_e32 v96, v232, v96
	v_mfma_f32_32x32x16_bf16 v[128:143], v[72:75], v[154:157], v[128:143]
	ds_read_b128 v[68:71], v208 offset:24576
	ds_read_b128 v[72:75], v208 offset:16384
	s_mov_b32 m0, s13
	s_nop 0
	global_load_lds_dwordx4 v188, s[60:61]
	v_add_f32_e32 v96, v234, v96
	v_add_f32_e32 v96, v210, v96
	v_add_f32_e32 v96, v235, v96
	v_exp_f32_e32 v244, v106
	v_exp_f32_e32 v245, v107
	s_waitcnt lgkmcnt(2)
	v_mfma_f32_32x32x16_bf16 v[112:127], v[236:239], v[150:153], v[112:127]
	v_exp_f32_e32 v246, v108
	v_exp_f32_e32 v247, v109
	v_exp_f32_e32 v248, v110
	v_exp_f32_e32 v111, v111
	v_cvt_pk_bf16_f32 v97, v175, v211
	v_cvt_pk_bf16_f32 v109, v244, v245
	v_cvt_pk_bf16_f32 v110, v246, v247
	v_mfma_f32_32x32x16_bf16 v[128:143], v[240:243], v[150:153], v[128:143]
	s_add_i32 m0, s13, 0x4400
	s_nop 0
	global_load_lds_dwordx4 v170, s[58:59]
	s_waitcnt lgkmcnt(0)
	v_mfma_f32_32x32x16_bf16 v[112:127], v[68:71], v[146:149], v[112:127]
	v_exp_f32_e32 v236, v98
	v_exp_f32_e32 v237, v99
	v_exp_f32_e32 v238, v100
	v_exp_f32_e32 v239, v101
	v_add_f32_e32 v96, v236, v96
	v_add_f32_e32 v96, v237, v96
	v_add_f32_e32 v96, v238, v96
	v_mfma_f32_32x32x16_bf16 v[128:143], v[72:75], v[146:149], v[128:143]
	s_add_i32 m0, s13, 0x400
	s_nop 0
	global_load_lds_dwordx4 v188, s[62:63]
	v_exp_f32_e32 v240, v102
	v_exp_f32_e32 v241, v103
	v_exp_f32_e32 v242, v104
	v_exp_f32_e32 v243, v105
	v_add_f32_e32 v96, v239, v96
	v_add_f32_e32 v96, v240, v96
	v_add_f32_e32 v96, v241, v96
	v_add_f32_e32 v96, v242, v96
	v_add_f32_e32 v96, v243, v96
	v_add_f32_e32 v96, v244, v96
	v_add_f32_e32 v96, v245, v96
	v_add_f32_e32 v96, v246, v96
	v_add_f32_e32 v96, v247, v96
	v_add_f32_e32 v96, v248, v96
	v_add_f32_e32 v208, v111, v96
	v_mov_b32_e32 v209, v208
	s_nop 1
	v_permlane32_swap_b32_e32 v208, v209
	v_cvt_pk_bf16_f32 v96, v172, v174
	v_cvt_pk_bf16_f32 v98, v212, v215
	v_cvt_pk_bf16_f32 v99, v216, v233
	v_cvt_pk_bf16_f32 v100, v173, v176
	v_cvt_pk_bf16_f32 v101, v177, v213
	v_cvt_pk_bf16_f32 v102, v214, v217
	v_cvt_pk_bf16_f32 v103, v232, v234
	v_cvt_pk_bf16_f32 v104, v210, v235
	v_cvt_pk_bf16_f32 v105, v236, v237
	v_cvt_pk_bf16_f32 v106, v238, v239
	v_cvt_pk_bf16_f32 v107, v240, v241
	v_cvt_pk_bf16_f32 v108, v242, v243
	v_cvt_pk_bf16_f32 v111, v248, v111
	v_add_u32_e32 v240, s48, v205
	ds_read_b64_tr_b16 v[210:211], v240 offset:0
	ds_read_b64_tr_b16 v[212:213], v240 offset:0x800
	ds_read_b64_tr_b16 v[214:215], v240 offset:0x1000
	ds_read_b64_tr_b16 v[216:217], v240 offset:0x1800
	ds_read_b64_tr_b16 v[232:233], v240 offset:0x2000
	ds_read_b64_tr_b16 v[234:235], v240 offset:0x2800
	ds_read_b64_tr_b16 v[236:237], v240 offset:0x3000
	ds_read_b64_tr_b16 v[238:239], v240 offset:0x3800
	s_waitcnt lgkmcnt(0)
; #define SBAR() __builtin_amdgcn_sched_barrier(0)
; template <int OFF> __device__ __forceinline__ s16x4 tr_read(int vb) { s16x4 r; asm volatile("ds_read_b64_tr_b16 %0, %1 offset:%2" : "=&v"(r) : "v"(vb), "i"(OFF) : "memory"); return r; }
; template <bool FIRST> __device__ __forceinline__ void partialSM(f32x16& p0, f32x16& p1, float& m_reg, f32x16& negm, float& alpha) {
;   float pmax = p0[0];
; #pragma unroll
;   for (int r = 1; r < 16; ++r) pmax = fmaxf(pmax, p0[r]);
; #pragma unroll
;   for (int r = 0; r < 16; ++r) pmax = fmaxf(pmax, p1[r]);
;   { auto rr = __builtin_amdgcn_permlane32_swap(__float_as_uint(pmax), __float_as_uint(pmax), false, false);
;     pmax = fmaxf(__uint_as_float(rr[0]), __uint_as_float(rr[1])); }
;   alpha = 1.f;
;   if (FIRST || __builtin_expect(__any(pmax > THR), 0)) { const float dl = FIRST ? pmax : fmaxf(pmax, 0.f); m_reg += dl; if (!FIRST) alpha = __builtin_amdgcn_exp2f(-dl);
; template <int D0> __device__ __forceinline__ void pv_one(f32x16& od, int vb, bf16x8 pa0, bf16x8 pa1, bf16x8 pa2, bf16x8 pa3) {
;   const s16x4 l0 = tr_read<v_rd_off(D0, 0, 0)>(vb), h0 = tr_read<v_rd_off(D0, 0, 1)>(vb), l1 = tr_read<v_rd_off(D0, 1, 0)>(vb), h1 = tr_read<v_rd_off(D0, 1, 1)>(vb);
;   const s16x4 l2 = tr_read<v_rd_off(D0, 2, 0)>(vb), h2 = tr_read<v_rd_off(D0, 2, 1)>(vb), l3 = tr_read<v_rd_off(D0, 3, 0)>(vb), h3 = tr_read<v_rd_off(D0, 3, 1)>(vb);
;   asm volatile("s_waitcnt lgkmcnt(0)" ::: "memory"); SBAR();
;   od = __builtin_amdgcn_mfma_f32_32x32x16_bf16(pa0, ATT_PK(l0, h0), od, 0, 0, 0);
;   od = __builtin_amdgcn_mfma_f32_32x32x16_bf16(pa1, ATT_PK(l1, h1), od, 0, 0, 0);
;   od = __builtin_amdgcn_mfma_f32_32x32x16_bf16(pa2, ATT_PK(l2, h2), od, 0, 0, 0);
;   od = __builtin_amdgcn_mfma_f32_32x32x16_bf16(pa3, ATT_PK(l3, h3), od, 0, 0, 0);
; }
; __device__ __forceinline__ void pv_d0(f32x16* o, int vb, bf16x8 pa0, bf16x8 pa1, bf16x8 pa2, bf16x8 pa3) {
;   pv_one<0>(o[0], vb, pa0, pa1, pa2, pa3); pv_one<1>(o[1], vb, pa0, pa1, pa2, pa3); pv_one<2>(o[2], vb, pa0, pa1, pa2, pa3); pv_one<3>(o[3], vb, pa0, pa1, pa2, pa3);
	s_nop 0
	v_mfma_f32_32x32x16_bf16 v[0:15], v[96:99], v[210:213], v[0:15]
	ds_read_b64_tr_b16 v[210:211], v240 offset:0x200
	ds_read_b64_tr_b16 v[212:213], v240 offset:0xa00
	v_mfma_f32_32x32x16_bf16 v[0:15], v[100:103], v[214:217], v[0:15]
	ds_read_b64_tr_b16 v[214:215], v240 offset:0x1200
	ds_read_b64_tr_b16 v[216:217], v240 offset:0x1a00
	v_mfma_f32_32x32x16_bf16 v[0:15], v[104:107], v[232:235], v[0:15]
	ds_read_b64_tr_b16 v[232:233], v240 offset:0x2200
	ds_read_b64_tr_b16 v[234:235], v240 offset:0x2a00
	v_mfma_f32_32x32x16_bf16 v[0:15], v[108:111], v[236:239], v[0:15]
	ds_read_b64_tr_b16 v[236:237], v240 offset:0x3200
	ds_read_b64_tr_b16 v[238:239], v240 offset:0x3a00
	s_waitcnt lgkmcnt(0)
	v_mfma_f32_32x32x16_bf16 v[48:63], v[96:99], v[210:213], v[48:63]
	ds_read_b64_tr_b16 v[210:211], v240 offset:0x400
	ds_read_b64_tr_b16 v[212:213], v240 offset:0xc00
	v_mfma_f32_32x32x16_bf16 v[48:63], v[100:103], v[214:217], v[48:63]
	ds_read_b64_tr_b16 v[214:215], v240 offset:0x1400
	ds_read_b64_tr_b16 v[216:217], v240 offset:0x1c00
	v_mfma_f32_32x32x16_bf16 v[48:63], v[104:107], v[232:235], v[48:63]
	ds_read_b64_tr_b16 v[232:233], v240 offset:0x2400
	ds_read_b64_tr_b16 v[234:235], v240 offset:0x2c00
	v_mfma_f32_32x32x16_bf16 v[48:63], v[108:111], v[236:239], v[48:63]
	ds_read_b64_tr_b16 v[236:237], v240 offset:0x3400
	ds_read_b64_tr_b16 v[238:239], v240 offset:0x3c00
	s_waitcnt lgkmcnt(0)
	v_mfma_f32_32x32x16_bf16 v[32:47], v[96:99], v[210:213], v[32:47]
	ds_read_b64_tr_b16 v[210:211], v240 offset:0x600
	ds_read_b64_tr_b16 v[212:213], v240 offset:0xe00
	v_mfma_f32_32x32x16_bf16 v[32:47], v[100:103], v[214:217], v[32:47]
	ds_read_b64_tr_b16 v[214:215], v240 offset:0x1600
	ds_read_b64_tr_b16 v[216:217], v240 offset:0x1e00
	v_mfma_f32_32x32x16_bf16 v[32:47], v[104:107], v[232:235], v[32:47]
	ds_read_b64_tr_b16 v[232:233], v240 offset:0x2600
	ds_read_b64_tr_b16 v[234:235], v240 offset:0x2e00
	v_mfma_f32_32x32x16_bf16 v[32:47], v[108:111], v[236:239], v[32:47]
	ds_read_b64_tr_b16 v[236:237], v240 offset:0x3600
	ds_read_b64_tr_b16 v[238:239], v240 offset:0x3e00
	s_waitcnt lgkmcnt(0)
	v_mfma_f32_32x32x16_bf16 v[16:31], v[96:99], v[210:213], v[16:31]
	v_max_f32_e32 v96, v129, v129
	v_max_f32_e32 v97, v128, v128
	v_max_f32_e32 v96, v97, v96
	v_max3_f32 v96, v96, v130, v131
	v_max3_f32 v96, v96, v132, v133
	v_max3_f32 v96, v96, v134, v135
	v_max3_f32 v96, v96, v136, v137
	v_mfma_f32_32x32x16_bf16 v[16:31], v[100:103], v[214:217], v[16:31]
	v_max3_f32 v96, v96, v138, v139
	v_max3_f32 v96, v96, v140, v141
	v_max3_f32 v96, v96, v142, v143
	v_max3_f32 v96, v96, v112, v113
	v_max3_f32 v96, v96, v114, v115
	v_max3_f32 v96, v96, v116, v117
	v_max3_f32 v96, v96, v118, v119
	v_mfma_f32_32x32x16_bf16 v[16:31], v[104:107], v[232:235], v[16:31]
	v_max3_f32 v96, v96, v120, v121
	v_max3_f32 v96, v96, v122, v123
	v_max3_f32 v96, v96, v124, v125
	v_max3_f32 v96, v96, v126, v127
	v_mov_b32_e32 v97, v96
	s_nop 1
	v_permlane32_swap_b32_e32 v96, v97
	v_mfma_f32_32x32x16_bf16 v[16:31], v[108:111], v[236:239], v[16:31]
	v_max_f32_e32 v96, v96, v97
	v_cmp_lt_f32_e32 vcc, s19, v96
	s_cbranch_vccnz .LBB0_215
	v_mov_b32_e32 v210, 1.0
	s_branch .LBB0_202
